# instruction selection: attention O/Q f32->bf16 packs via v_cvt_pk_bf16_f32 instead of the integer RNE bit trick, K-fragment LDS reads hoisted; on top of seam+prologue edits
# speedup vs baseline: 1.0075x; 1.0075x over previous
; #define LAS __attribute__((address_space(3)))
; __device__ __forceinline__ unsigned pk2(float lo, float hi) { return f2bf(lo) | (f2bf(hi) << 16); }
; __device__ __forceinline__ float bflo(unsigned w) { return __uint_as_float(w << 16); }
; __device__ __forceinline__ float bfhi(unsigned w) { return __uint_as_float(w & 0xffff0000u); }
; #define ATT_LOAD_Q(A) do { const size_t qrw_ = qrow0 + (A) * 16; const bf16* qp_ = QKV + qrw_ * QKVW + (qrw_ >> 8) * adjq + qh * 64 + fq * 8; qw0 = *(const u32x4*)qp_; qw1 = *(const u32x4*)(qp_ + 32); \
;         const f32x4* rp_ = (const f32x4*)(rope + (size_t)(nb * 128 + (A) * 16 + fr) * 16); _Pragma("unroll") for (int c = 0; c < 4; ++c) qr[c] = rp_[c]; } while (0)
; __device__ __forceinline__ void attn_phase(LAS unsigned char* lds, const bf16* QKV, bf16* O, const float* rope, const float* sinks) {
;     ...
;             { u32x4 w0 = qw0; const u32x4 w1 = qw1;
;               const float cs[8] = {qr[0][0], qr[0][2], qr[1][0], qr[1][2], qr[2][0], qr[2][2], qr[3][0], qr[3][2]}, sn[8] = {qr[0][1], qr[0][3], qr[1][1], qr[1][3], qr[2][1], qr[2][3], qr[3][1], qr[3][3]};
;               u32x4 pw; pw.x = __shfl_xor(w0.x, 16); pw.y = __shfl_xor(w0.y, 16); pw.z = __shfl_xor(w0.z, 16); pw.w = __shfl_xor(w0.w, 16);
;               const float sg = fq == 0 ? -1.f : 1.f;
;               u32x4 rw;
; #pragma unroll
;               for (int e = 0; e < 4; ++e) { const float xa = bflo(w0[e]), xb = bfhi(w0[e]), pa = bflo(pw[e]), pb = bfhi(pw[e]);
;                   rw[e] = pk2(xa * cs[2 * e] + sg * pa * sn[2 * e], xb * cs[2 * e + 1] + sg * pb * sn[2 * e + 1]); }
;               if (fq < 2) w0 = rw;
;               qf[0] = __builtin_bit_cast(bf16x8, w0); qf[1] = __builtin_bit_cast(bf16x8, w1); }
;             if (a < 7) ATT_LOAD_Q(a + 1);
;             f32x4 sc[10];
; #pragma unroll
;             for (int j = 0; j < 10; ++j) { const LAS bf16* kp = Kl + ((a + j) * 16 + fr) * KP + fq * 8;
;                 f32x4 z = (f32x4){0.f, 0.f, 0.f, 0.f};
;                 z = __builtin_amdgcn_mfma_f32_16x16x32_bf16(*(const LAS bf16x8*)kp, qf[0], z, 0, 0, 0);
;                 z = __builtin_amdgcn_mfma_f32_16x16x32_bf16(*(const LAS bf16x8*)(kp + 32), qf[1], z, 0, 0, 0);
;                 sc[j] = z; }
.LBB0_1748:
	s_waitcnt lgkmcnt(2)
	v_lshlrev_b32_e32 v133, 16, v127
	v_lshlrev_b32_e32 v132, 16, v126
	v_and_b32_e32 v127, 0xffff0000, v127
	v_and_b32_e32 v126, 0xffff0000, v126
	v_mov_b32_e32 v135, v92
	v_mov_b32_e32 v92, v97
	v_mov_b32_e32 v97, v94
	v_pk_mul_f32 v[126:127], v[104:105], v[126:127]
	v_mov_b32_e32 v94, v99
	v_and_b32_e32 v131, 0xffff0000, v81
	v_and_b32_e32 v130, 0xffff0000, v80
	v_mov_b32_e32 v134, v96
	v_pk_mul_f32 v[132:133], v[104:105], v[132:133]
	v_mov_b32_e32 v96, v98
	v_pk_mul_f32 v[94:95], v[94:95], v[126:127]
	s_waitcnt lgkmcnt(0)
	v_or_b32_e32 v165, s28, v34
	v_mad_u64_u32 v[166:167], s[100:101], v165, s42, v[106:107]
	ds_read_b128 v[168:171], v166 offset:0
	ds_read_b128 v[172:175], v166 offset:64
	ds_read_b128 v[176:179], v166 offset:2304
	ds_read_b128 v[180:183], v166 offset:2368
	ds_read_b128 v[184:187], v166 offset:4608
	ds_read_b128 v[188:191], v166 offset:4672
	ds_read_b128 v[192:195], v166 offset:6912
	ds_read_b128 v[196:199], v166 offset:6976
	ds_read_b128 v[202:205], v166 offset:9216
	ds_read_b128 v[206:209], v166 offset:9280
	ds_read_b128 v[210:213], v166 offset:11520
	ds_read_b128 v[214:217], v166 offset:11584
	ds_read_b128 v[218:221], v166 offset:13824
	ds_read_b128 v[222:225], v166 offset:13888
	ds_read_b128 v[226:229], v166 offset:16128
	ds_read_b128 v[230:233], v166 offset:16192
	ds_read_b128 v[234:237], v166 offset:18432
	ds_read_b128 v[238:241], v166 offset:18496
	ds_read_b128 v[242:245], v166 offset:20736
	ds_read_b128 v[246:249], v166 offset:20800
	v_lshlrev_b32_e32 v127, 16, v125
	v_lshlrev_b32_e32 v126, 16, v115
	v_lshlrev_b32_e32 v129, 16, v81
	v_lshlrev_b32_e32 v128, 16, v80
	v_pk_mul_f32 v[92:93], v[92:93], v[132:133]
	v_pk_fma_f32 v[94:95], v[96:97], v[130:131], v[94:95]
	v_mov_b32_e32 v131, v84
	v_pk_mul_f32 v[126:127], v[104:105], v[126:127]
	v_mov_b32_e32 v84, v89
	v_pk_fma_f32 v[92:93], v[134:135], v[128:129], v[92:93]
	v_lshlrev_b32_e32 v97, 16, v83
	v_lshlrev_b32_e32 v96, 16, v82
	v_and_b32_e32 v129, 0xffff0000, v125
	v_and_b32_e32 v128, 0xffff0000, v115
	v_mov_b32_e32 v130, v88
	v_pk_mul_f32 v[84:85], v[84:85], v[126:127]
	v_mov_b32_e32 v89, v86
	v_pk_fma_f32 v[84:85], v[130:131], v[96:97], v[84:85]
	v_pk_mul_f32 v[96:97], v[104:105], v[128:129]
	v_mov_b32_e32 v86, v91
	v_and_b32_e32 v99, 0xffff0000, v83
	v_and_b32_e32 v98, 0xffff0000, v82
	v_mov_b32_e32 v88, v90
	v_pk_mul_f32 v[86:87], v[86:87], v[96:97]
	v_or_b32_e32 v113, s28, v34
	v_pk_fma_f32 v[86:87], v[88:89], v[98:99], v[86:87]
	v_cvt_pk_bf16_f32 v88, v92, v94
	v_cvt_pk_bf16_f32 v89, v93, v95
	v_cvt_pk_bf16_f32 v90, v84, v86
	v_cvt_pk_bf16_f32 v91, v85, v87
	v_cndmask_b32_e64 v95, v83, v91, s[8:9]
	v_cndmask_b32_e64 v94, v82, v90, s[8:9]
	v_cndmask_b32_e64 v93, v81, v89, s[8:9]
	v_cndmask_b32_e64 v92, v80, v88, s[8:9]
	s_add_i32 s45, s50, 1
	s_lshl_b32 s54, s45, 4
	v_or_b32_e32 v88, s54, v34
	v_mad_u64_u32 v[126:127], s[18:19], v88, s42, v[106:107]
	s_waitcnt lgkmcnt(15)
	v_mfma_f32_16x16x32_bf16 v[84:87], v[168:171], v[92:95], 0
	s_add_i32 s49, s28, 32
	s_add_i32 s56, s28, 48
	s_waitcnt lgkmcnt(15)
	v_mfma_f32_16x16x32_bf16 v[96:99], v[172:175], v[76:79], v[84:87]
	s_add_i32 s48, s28, 64
	s_add_i32 s53, s28, 0x50
	s_waitcnt lgkmcnt(15)
	v_mfma_f32_16x16x32_bf16 v[84:87], v[176:179], v[92:95], 0
	v_or_b32_e32 v88, s56, v34
	v_mad_u64_u32 v[134:135], s[18:19], v88, s42, v[106:107]
	s_waitcnt lgkmcnt(15)
	v_mfma_f32_16x16x32_bf16 v[126:129], v[180:183], v[76:79], v[84:87]
	v_or_b32_e32 v80, s49, v34
	s_add_i32 s47, s28, 0x60
	s_add_i32 s52, s28, 0x70
	s_nop 0
	v_mad_u64_u32 v[84:85], s[18:19], v80, s42, v[106:107]
	s_waitcnt lgkmcnt(15)
	v_mfma_f32_16x16x32_bf16 v[80:83], v[184:187], v[92:95], 0
	s_add_i32 s46, s28, 0x80
	s_add_i32 s51, s28, 0x90
	s_waitcnt lgkmcnt(14)
	v_mfma_f32_16x16x32_bf16 v[130:133], v[188:191], v[76:79], v[80:83]
	v_or_b32_e32 v115, s51, v34
	v_mad_u64_u32 v[154:155], s[18:19], v115, s42, v[106:107]
	s_nop 0
	s_waitcnt lgkmcnt(13)
	v_mfma_f32_16x16x32_bf16 v[84:87], v[192:195], v[92:95], 0
	v_or_b32_e32 v88, s53, v34
	v_mad_u64_u32 v[142:143], s[18:19], v88, s42, v[106:107]
	s_waitcnt lgkmcnt(12)
	v_mfma_f32_16x16x32_bf16 v[134:137], v[196:199], v[76:79], v[84:87]
	v_or_b32_e32 v80, s48, v34
	s_nop 2
	v_mad_u64_u32 v[84:85], s[18:19], v80, s42, v[106:107]
	s_waitcnt lgkmcnt(11)
	v_mfma_f32_16x16x32_bf16 v[80:83], v[202:205], v[92:95], 0
	v_mul_f32_e32 v115, 0x3e000000, v127
	v_mul_f32_e32 v127, 0x3e000000, v130
	s_waitcnt lgkmcnt(10)
	v_mfma_f32_16x16x32_bf16 v[138:141], v[206:209], v[76:79], v[80:83]
	v_or_b32_e32 v130, s56, v108
	s_nop 1
	s_waitcnt lgkmcnt(9)
	v_mfma_f32_16x16x32_bf16 v[84:87], v[210:213], v[92:95], 0
	v_or_b32_e32 v88, s52, v34
	v_mad_u64_u32 v[150:151], s[18:19], v88, s42, v[106:107]
	s_waitcnt lgkmcnt(8)
	v_mfma_f32_16x16x32_bf16 v[142:145], v[214:217], v[76:79], v[84:87]
	v_or_b32_e32 v80, s47, v34
	s_nop 2
	v_mad_u64_u32 v[84:85], s[18:19], v80, s42, v[106:107]
	s_waitcnt lgkmcnt(7)
	v_mfma_f32_16x16x32_bf16 v[80:83], v[218:221], v[92:95], 0
	s_waitcnt lgkmcnt(6)
	v_mfma_f32_16x16x32_bf16 v[88:91], v[222:225], v[76:79], v[80:83]
	s_nop 4
	s_waitcnt lgkmcnt(5)
	v_mfma_f32_16x16x32_bf16 v[84:87], v[226:229], v[92:95], 0
	v_mul_f32_e32 v88, 0x3e000000, v88
	v_mul_f32_e32 v89, 0x3e000000, v89
	v_mul_f32_e32 v90, 0x3e000000, v90
	s_waitcnt lgkmcnt(4)
	v_mfma_f32_16x16x32_bf16 v[84:87], v[230:233], v[76:79], v[84:87]
	v_or_b32_e32 v80, s46, v34
	v_mad_u64_u32 v[146:147], s[18:19], v80, s42, v[106:107]
	s_waitcnt lgkmcnt(3)
	v_mfma_f32_16x16x32_bf16 v[80:83], v[234:237], v[92:95], 0
	v_mul_f32_e32 v91, 0x3e000000, v91
	v_mul_f32_e32 v84, 0x3e000000, v84
	s_waitcnt lgkmcnt(2)
; #define LAS __attribute__((address_space(3)))
; __device__ __forceinline__ void attn_phase(LAS unsigned char* lds, const bf16* QKV, bf16* O, const float* rope, const float* sinks) {
;     ...
;             for (int j = 0; j < 10; ++j) { const LAS bf16* kp = Kl + ((a + j) * 16 + fr) * KP + fq * 8;
;                 f32x4 z = (f32x4){0.f, 0.f, 0.f, 0.f};
;                 z = __builtin_amdgcn_mfma_f32_16x16x32_bf16(*(const LAS bf16x8*)kp, qf[0], z, 0, 0, 0);
;                 z = __builtin_amdgcn_mfma_f32_16x16x32_bf16(*(const LAS bf16x8*)(kp + 32), qf[1], z, 0, 0, 0);
;                 sc[j] = z; }
;             const int qpos = 128 + qi; float mx = -INFINITY;
; #pragma unroll
;             for (int j = 0; j < 10; ++j)
; #pragma unroll
;                 for (int e = 0; e < 4; ++e) { const int kpos = (a + j) * 16 + 4 * fq + e; const bool valid = (kpos <= qpos) && (kpos > qpos - 128) && (nb > 0 || kpos >= 128);
;                     const float sv = valid ? sc[j][e] * 0.125f : -INFINITY; sc[j][e] = sv; mx = fmaxf(mx, sv); }
	v_mfma_f32_16x16x32_bf16 v[80:83], v[238:241], v[76:79], v[80:83]
	v_mul_f32_e32 v85, 0x3e000000, v85
	v_mul_f32_e32 v86, 0x3e000000, v86
	s_waitcnt lgkmcnt(1)
	v_mfma_f32_16x16x32_bf16 v[92:95], v[242:245], v[92:95], 0
	v_mul_f32_e32 v87, 0x3e000000, v87
	s_nop 1
	v_mul_f32_e32 v80, 0x3e000000, v80
	v_mul_f32_e32 v82, 0x3e000000, v82
	s_waitcnt lgkmcnt(0)
	v_mfma_f32_16x16x32_bf16 v[76:79], v[246:249], v[76:79], v[92:95]
	s_nop 2
	v_or_b32_e32 v93, s28, v108
	v_mul_f32_e32 v95, 0x3e000000, v97
	v_or_b32_e32 v97, 2, v93
	v_cmp_gt_u32_e32 vcc, v97, v113
	v_mul_f32_e32 v97, 0x3e000000, v98
	s_and_b64 vcc, s[36:37], vcc
	v_or_b32_e32 v93, 3, v93
	v_cndmask_b32_e32 v97, v124, v97, vcc
	v_cmp_gt_u32_e32 vcc, v93, v113
	v_or_b32_e32 v92, 0x80, v113
	v_mul_f32_e32 v93, 0x3e000000, v99
	s_and_b64 vcc, s[36:37], vcc
	v_or_b32_e32 v98, s54, v108
	v_cndmask_b32_e32 v93, v124, v93, vcc
	v_cmp_le_u32_e32 vcc, v98, v92
	v_cmp_gt_u32_e64 s[18:19], v98, v113
	s_and_b64 s[18:19], vcc, s[18:19]
	s_cmp_gt_u32 s50, 6
	s_cselect_b64 s[54:55], -1, 0
	s_or_b64 s[54:55], s[36:37], s[54:55]
	v_mul_f32_e32 v99, 0x3e000000, v126
	s_and_b64 vcc, s[18:19], s[54:55]
	v_cndmask_b32_e32 v99, v124, v99, vcc
	v_cmp_lt_u32_e32 vcc, v98, v92
	v_cmp_ge_u32_e64 s[18:19], v98, v113
	s_and_b64 s[18:19], vcc, s[18:19]
	s_and_b64 vcc, s[18:19], s[54:55]
	v_or_b32_e32 v125, 2, v98
	v_cndmask_b32_e32 v115, v124, v115, vcc
	v_cmp_le_u32_e32 vcc, v125, v92
	v_cmp_gt_u32_e64 s[18:19], v125, v113
	s_and_b64 s[18:19], vcc, s[18:19]
	v_mul_f32_e32 v125, 0x3e000000, v128
	s_and_b64 vcc, s[18:19], s[54:55]
	v_or_b32_e32 v98, 3, v98
	v_cndmask_b32_e32 v125, v124, v125, vcc
	v_cmp_le_u32_e32 vcc, v98, v92
	v_cmp_gt_u32_e64 s[18:19], v98, v113
	s_and_b64 s[18:19], vcc, s[18:19]
	v_mul_f32_e32 v98, 0x3e000000, v129
	s_and_b64 vcc, s[18:19], s[54:55]
	v_or_b32_e32 v126, s49, v108
	v_cndmask_b32_e32 v98, v124, v98, vcc
	v_cmp_le_u32_e32 vcc, v126, v92
	v_cmp_gt_u32_e64 s[18:19], v126, v113
	s_and_b64 s[18:19], vcc, s[18:19]
	s_cmpk_gt_u32 s28, 0x5f
	s_cselect_b64 s[54:55], -1, 0
	s_or_b64 s[54:55], s[36:37], s[54:55]
	s_and_b64 vcc, s[54:55], s[18:19]
	v_cndmask_b32_e32 v127, v124, v127, vcc
	v_cmp_lt_u32_e32 vcc, v126, v92
	v_cmp_ge_u32_e64 s[18:19], v126, v113
	s_and_b64 s[18:19], vcc, s[18:19]
	v_mul_f32_e32 v128, 0x3e000000, v131
	s_and_b64 vcc, s[54:55], s[18:19]
	v_or_b32_e32 v129, 2, v126
	v_cndmask_b32_e32 v128, v124, v128, vcc
	v_cmp_le_u32_e32 vcc, v129, v92
	v_cmp_gt_u32_e64 s[18:19], v129, v113
	s_and_b64 s[18:19], vcc, s[18:19]
	v_mul_f32_e32 v129, 0x3e000000, v132
	s_and_b64 vcc, s[54:55], s[18:19]
	v_or_b32_e32 v126, 3, v126
	v_cndmask_b32_e32 v129, v124, v129, vcc
	v_cmp_le_u32_e32 vcc, v126, v92
	v_cmp_gt_u32_e64 s[18:19], v126, v113
	s_and_b64 s[18:19], vcc, s[18:19]
	v_mul_f32_e32 v126, 0x3e000000, v133
	s_and_b64 vcc, s[54:55], s[18:19]
	v_cndmask_b32_e32 v126, v124, v126, vcc
	v_cmp_le_u32_e32 vcc, v130, v92
	v_cmp_gt_u32_e64 s[18:19], v130, v113
	s_and_b64 s[18:19], vcc, s[18:19]
	s_cmpk_gt_u32 s28, 0x4f
	s_cselect_b64 s[54:55], -1, 0
	s_or_b64 s[54:55], s[36:37], s[54:55]
	v_mul_f32_e32 v131, 0x3e000000, v134
	s_and_b64 vcc, s[54:55], s[18:19]
	v_cndmask_b32_e32 v131, v124, v131, vcc
	v_cmp_lt_u32_e32 vcc, v130, v92
	v_cmp_ge_u32_e64 s[18:19], v130, v113
	s_and_b64 s[18:19], vcc, s[18:19]
	v_mul_f32_e32 v132, 0x3e000000, v135
	s_and_b64 vcc, s[54:55], s[18:19]
	v_or_b32_e32 v133, 2, v130
	v_cndmask_b32_e32 v132, v124, v132, vcc
	v_cmp_le_u32_e32 vcc, v133, v92
	v_cmp_gt_u32_e64 s[18:19], v133, v113
	s_and_b64 s[18:19], vcc, s[18:19]
	v_mul_f32_e32 v133, 0x3e000000, v136
	s_and_b64 vcc, s[54:55], s[18:19]
	v_or_b32_e32 v130, 3, v130
	v_cndmask_b32_e32 v133, v124, v133, vcc
	v_cmp_le_u32_e32 vcc, v130, v92
	v_cmp_gt_u32_e64 s[18:19], v130, v113
	s_and_b64 s[18:19], vcc, s[18:19]
	v_mul_f32_e32 v130, 0x3e000000, v137
	s_and_b64 vcc, s[54:55], s[18:19]
	v_or_b32_e32 v134, s48, v108
	v_cndmask_b32_e32 v130, v124, v130, vcc
	v_cmp_le_u32_e32 vcc, v134, v92
	v_cmp_gt_u32_e64 s[18:19], v134, v113
	s_and_b64 s[18:19], vcc, s[18:19]
	s_cmp_gt_u32 s28, 63
	s_cselect_b64 s[54:55], -1, 0
	s_or_b64 s[54:55], s[36:37], s[54:55]
	v_mul_f32_e32 v135, 0x3e000000, v138
	s_and_b64 vcc, s[54:55], s[18:19]
	v_cndmask_b32_e32 v135, v124, v135, vcc
	v_cmp_lt_u32_e32 vcc, v134, v92
	v_cmp_ge_u32_e64 s[18:19], v134, v113
	s_and_b64 s[18:19], vcc, s[18:19]
	v_mul_f32_e32 v136, 0x3e000000, v139
	s_and_b64 vcc, s[54:55], s[18:19]
	v_or_b32_e32 v137, 2, v134
	v_cndmask_b32_e32 v136, v124, v136, vcc
	v_cmp_le_u32_e32 vcc, v137, v92
	v_cmp_gt_u32_e64 s[18:19], v137, v113
	s_and_b64 s[18:19], vcc, s[18:19]
	v_mul_f32_e32 v137, 0x3e000000, v140
	s_and_b64 vcc, s[54:55], s[18:19]
	v_or_b32_e32 v134, 3, v134
	v_cndmask_b32_e32 v137, v124, v137, vcc
	v_cmp_le_u32_e32 vcc, v134, v92
	v_cmp_gt_u32_e64 s[18:19], v134, v113
	s_and_b64 s[18:19], vcc, s[18:19]
	v_mul_f32_e32 v134, 0x3e000000, v141
	s_and_b64 vcc, s[54:55], s[18:19]
	v_or_b32_e32 v138, s53, v108
	v_cndmask_b32_e32 v134, v124, v134, vcc
	v_cmp_le_u32_e32 vcc, v138, v92
	v_cmp_gt_u32_e64 s[18:19], v138, v113
	s_and_b64 s[18:19], vcc, s[18:19]
	s_cmp_gt_u32 s28, 47
	s_cselect_b64 s[54:55], -1, 0
	s_or_b64 s[54:55], s[36:37], s[54:55]
	v_mul_f32_e32 v139, 0x3e000000, v142
	s_and_b64 vcc, s[54:55], s[18:19]
	v_cndmask_b32_e32 v139, v124, v139, vcc
	v_cmp_lt_u32_e32 vcc, v138, v92
	v_cmp_ge_u32_e64 s[18:19], v138, v113
	s_and_b64 s[18:19], vcc, s[18:19]
	v_mul_f32_e32 v140, 0x3e000000, v143
	s_and_b64 vcc, s[54:55], s[18:19]
	v_or_b32_e32 v141, 2, v138
	v_cndmask_b32_e32 v140, v124, v140, vcc
	v_cmp_le_u32_e32 vcc, v141, v92
	v_cmp_gt_u32_e64 s[18:19], v141, v113
; __device__ __forceinline__ void attn_phase(LAS unsigned char* lds, const bf16* QKV, bf16* O, const float* rope, const float* sinks) {
;     ...
;             const int qpos = 128 + qi; float mx = -INFINITY;
; #pragma unroll
;             for (int j = 0; j < 10; ++j)
; #pragma unroll
;                 for (int e = 0; e < 4; ++e) { const int kpos = (a + j) * 16 + 4 * fq + e; const bool valid = (kpos <= qpos) && (kpos > qpos - 128) && (nb > 0 || kpos >= 128);
;                     const float sv = valid ? sc[j][e] * 0.125f : -INFINITY; sc[j][e] = sv; mx = fmaxf(mx, sv); }
;             mx = fmaxf(mx, __shfl_xor(mx, 16)); mx = fmaxf(mx, __shfl_xor(mx, 32)); mx = fmaxf(mx, sink);
;             float l = 0.f;
; #pragma unroll
;             for (int j = 0; j < 10; ++j)
; #pragma unroll
;                 for (int e = 0; e < 4; ++e) { const float p = __expf(sc[j][e] - mx); sc[j][e] = p; l += p; }
;             l += __shfl_xor(l, 16); l += __shfl_xor(l, 32); l += __expf(sink - mx);
	s_and_b64 s[18:19], vcc, s[18:19]
	v_mul_f32_e32 v141, 0x3e000000, v144
	s_and_b64 vcc, s[54:55], s[18:19]
	v_or_b32_e32 v138, 3, v138
	v_cndmask_b32_e32 v141, v124, v141, vcc
	v_cmp_le_u32_e32 vcc, v138, v92
	v_cmp_gt_u32_e64 s[18:19], v138, v113
	s_and_b64 s[18:19], vcc, s[18:19]
	v_mul_f32_e32 v138, 0x3e000000, v145
	s_and_b64 vcc, s[54:55], s[18:19]
	v_or_b32_e32 v142, s47, v108
	v_cndmask_b32_e32 v138, v124, v138, vcc
	v_cmp_le_u32_e32 vcc, v142, v92
	v_cmp_gt_u32_e64 s[18:19], v142, v113
	s_and_b64 s[18:19], vcc, s[18:19]
	s_cmp_gt_u32 s28, 31
	s_cselect_b64 s[54:55], -1, 0
	s_or_b64 s[54:55], s[36:37], s[54:55]
	s_and_b64 vcc, s[54:55], s[18:19]
	v_cndmask_b32_e32 v88, v124, v88, vcc
	v_cmp_lt_u32_e32 vcc, v142, v92
	v_cmp_ge_u32_e64 s[18:19], v142, v113
	s_and_b64 s[18:19], vcc, s[18:19]
	s_and_b64 vcc, s[54:55], s[18:19]
	v_or_b32_e32 v143, 2, v142
	v_cndmask_b32_e32 v89, v124, v89, vcc
	v_cmp_le_u32_e32 vcc, v143, v92
	v_cmp_gt_u32_e64 s[18:19], v143, v113
	s_and_b64 s[18:19], vcc, s[18:19]
	s_and_b64 vcc, s[54:55], s[18:19]
	v_or_b32_e32 v142, 3, v142
	v_cndmask_b32_e32 v90, v124, v90, vcc
	v_cmp_le_u32_e32 vcc, v142, v92
	v_cmp_gt_u32_e64 s[18:19], v142, v113
	s_and_b64 s[18:19], vcc, s[18:19]
	s_and_b64 vcc, s[54:55], s[18:19]
	v_or_b32_e32 v142, s52, v108
	v_cndmask_b32_e32 v91, v124, v91, vcc
	v_cmp_le_u32_e32 vcc, v142, v92
	v_cmp_gt_u32_e64 s[18:19], v142, v113
	s_and_b64 s[18:19], vcc, s[18:19]
	v_mul_f32_e32 v94, 0x3e000000, v96
	s_cmp_lg_u32 s28, 0
	v_cndmask_b32_e64 v94, v124, v94, s[14:15]
	v_cndmask_b32_e64 v95, v124, v95, s[16:17]
	s_cselect_b64 s[52:53], -1, 0
	v_max3_f32 v96, v94, s43, v95
	s_or_b64 s[52:53], s[36:37], s[52:53]
	v_max3_f32 v96, v96, v97, v93
	s_and_b64 vcc, s[52:53], s[18:19]
	v_max3_f32 v96, v96, v99, v115
	v_cndmask_b32_e32 v84, v124, v84, vcc
	v_cmp_lt_u32_e32 vcc, v142, v92
	v_cmp_ge_u32_e64 s[18:19], v142, v113
	v_max3_f32 v96, v96, v125, v98
	s_and_b64 s[18:19], vcc, s[18:19]
	v_max3_f32 v96, v96, v127, v128
	s_and_b64 vcc, s[52:53], s[18:19]
	v_or_b32_e32 v143, 2, v142
	v_max3_f32 v96, v96, v129, v126
	v_cndmask_b32_e32 v85, v124, v85, vcc
	v_cmp_le_u32_e32 vcc, v143, v92
	v_cmp_gt_u32_e64 s[18:19], v143, v113
	v_max3_f32 v96, v96, v131, v132
	s_and_b64 s[18:19], vcc, s[18:19]
	v_max3_f32 v96, v96, v133, v130
	s_and_b64 vcc, s[52:53], s[18:19]
	v_or_b32_e32 v142, 3, v142
	v_max3_f32 v96, v96, v135, v136
	v_cndmask_b32_e32 v86, v124, v86, vcc
	v_cmp_le_u32_e32 vcc, v142, v92
	v_cmp_gt_u32_e64 s[18:19], v142, v113
	v_max3_f32 v96, v96, v137, v134
	s_and_b64 s[18:19], vcc, s[18:19]
	v_max3_f32 v96, v96, v139, v140
	s_and_b64 vcc, s[52:53], s[18:19]
	v_or_b32_e32 v113, s46, v108
	v_max3_f32 v96, v96, v141, v138
	v_cndmask_b32_e32 v87, v124, v87, vcc
	v_cmp_le_u32_e32 vcc, v113, v92
	v_max3_f32 v96, v96, v88, v89
	v_max3_f32 v96, v96, v90, v91
	v_cndmask_b32_e32 v142, v124, v80, vcc
	v_mul_f32_e32 v80, 0x3e000000, v81
	v_cmp_lt_u32_e32 vcc, v113, v92
	v_or_b32_e32 v81, 2, v113
	v_max3_f32 v96, v96, v84, v85
	v_cndmask_b32_e32 v143, v124, v80, vcc
	v_cmp_le_u32_e32 vcc, v81, v92
	v_or_b32_e32 v81, 3, v113
	v_max3_f32 v96, v96, v86, v87
	v_cndmask_b32_e32 v144, v124, v82, vcc
	v_mul_f32_e32 v82, 0x3e000000, v83
	v_cmp_le_u32_e32 vcc, v81, v92
	v_or_b32_e32 v81, s51, v108
	v_mul_f32_e32 v76, 0x3e000000, v76
	v_cndmask_b32_e32 v113, v124, v82, vcc
	v_cmp_le_u32_e32 vcc, v81, v92
	v_max3_f32 v80, v96, v142, v143
	v_max3_f32 v80, v80, v144, v113
	v_cndmask_b32_e32 v145, v124, v76, vcc
	v_mul_f32_e32 v76, 0x3e000000, v77
	v_cmp_lt_u32_e32 vcc, v81, v92
	v_mul_f32_e32 v78, 0x3e000000, v78
	v_mul_f32_e32 v79, 0x3e000000, v79
	v_cndmask_b32_e32 v77, v124, v76, vcc
	v_max3_f32 v76, v80, v145, v77
	v_or_b32_e32 v80, 2, v81
	v_cmp_le_u32_e32 vcc, v80, v92
	s_cmp_eq_u32 s45, 8
	s_mov_b32 s50, s45
	v_cndmask_b32_e32 v146, v124, v78, vcc
	v_or_b32_e32 v78, 3, v81
	v_cmp_le_u32_e32 vcc, v78, v92
	s_nop 1
	v_cndmask_b32_e32 v147, v124, v79, vcc
	v_max3_f32 v76, v76, v146, v147
	ds_bpermute_b32 v78, v111, v76
	s_waitcnt lgkmcnt(0)
	v_max_f32_e32 v78, v78, v78
	v_max_f32_e32 v76, v76, v78
	ds_bpermute_b32 v78, v120, v76
	s_waitcnt vmcnt(0) lgkmcnt(0)
	v_max3_f32 v76, v76, v78, v117
	v_sub_f32_e32 v79, v95, v76
	v_sub_f32_e32 v95, v127, v76
	v_mul_f32_e32 v95, 0x3fb8aa3b, v95
	v_sub_f32_e32 v78, v94, v76
	v_sub_f32_e32 v94, v98, v76
	v_exp_f32_e32 v98, v95
	v_sub_f32_e32 v95, v128, v76
	v_mul_f32_e32 v95, 0x3fb8aa3b, v95
	v_sub_f32_e32 v83, v99, v76
	v_exp_f32_e32 v99, v95
	v_sub_f32_e32 v95, v129, v76
	v_mul_f32_e32 v95, 0x3fb8aa3b, v95
	v_sub_f32_e32 v92, v115, v76
	v_exp_f32_e32 v115, v95
	v_sub_f32_e32 v95, v126, v76
	v_mul_f32_e32 v95, 0x3fb8aa3b, v95
	v_mul_f32_e32 v78, 0x3fb8aa3b, v78
	v_sub_f32_e32 v82, v93, v76
	v_sub_f32_e32 v93, v125, v76
	v_exp_f32_e32 v125, v95
	v_sub_f32_e32 v95, v131, v76
	v_exp_f32_e32 v78, v78
	v_mul_f32_e32 v79, 0x3fb8aa3b, v79
	v_sub_f32_e32 v80, v97, v76
	v_mul_f32_e32 v95, 0x3fb8aa3b, v95
	v_exp_f32_e32 v79, v79
	v_mul_f32_e32 v80, 0x3fb8aa3b, v80
	v_exp_f32_e32 v126, v95
	v_sub_f32_e32 v95, v132, v76
	v_exp_f32_e32 v80, v80
	v_mul_f32_e32 v82, 0x3fb8aa3b, v82
	v_mul_f32_e32 v95, 0x3fb8aa3b, v95
	v_exp_f32_e32 v82, v82
	v_mul_f32_e32 v83, 0x3fb8aa3b, v83
	v_exp_f32_e32 v127, v95
	v_sub_f32_e32 v95, v133, v76
	v_add_f32_e32 v81, 0, v78
	v_exp_f32_e32 v83, v83
	v_mul_f32_e32 v92, 0x3fb8aa3b, v92
	v_mul_f32_e32 v95, 0x3fb8aa3b, v95
	v_add_f32_e32 v81, v79, v81
	v_exp_f32_e32 v92, v92
	v_mul_f32_e32 v93, 0x3fb8aa3b, v93
	v_exp_f32_e32 v128, v95
	v_sub_f32_e32 v95, v130, v76
	v_add_f32_e32 v81, v80, v81
	v_exp_f32_e32 v93, v93
	v_mul_f32_e32 v94, 0x3fb8aa3b, v94
; #define LAS __attribute__((address_space(3)))
; __device__ __forceinline__ unsigned pk2(float lo, float hi) { return f2bf(lo) | (f2bf(hi) << 16); }
; __device__ __forceinline__ s16x4 tr_read(const LAS bf16* p) { return __builtin_bit_cast(s16x4, __builtin_amdgcn_ds_read_tr16_b64_v4i16((LAS s16x4*)p)); }
; __device__ __forceinline__ void attn_phase(LAS unsigned char* lds, const bf16* QKV, bf16* O, const float* rope, const float* sinks) {
;     ...
;             float l = 0.f;
; #pragma unroll
;             for (int j = 0; j < 10; ++j)
; #pragma unroll
;                 for (int e = 0; e < 4; ++e) { const float p = __expf(sc[j][e] - mx); sc[j][e] = p; l += p; }
;             l += __shfl_xor(l, 16); l += __shfl_xor(l, 32); l += __expf(sink - mx);
;             const float rl = 1.0f / l;
;             f32x4 oacc[4];
; #pragma unroll
;             for (int c = 0; c < 4; ++c) oacc[c] = (f32x4){0.f, 0.f, 0.f, 0.f};
; #pragma unroll
;             for (int j2 = 0; j2 < 5; ++j2) {
;                 u32x4 pwv; pwv.x = pk2(sc[2 * j2][0], sc[2 * j2][1]); pwv.y = pk2(sc[2 * j2][2], sc[2 * j2][3]); pwv.z = pk2(sc[2 * j2 + 1][0], sc[2 * j2 + 1][1]); pwv.w = pk2(sc[2 * j2 + 1][2], sc[2 * j2 + 1][3]);
;                 const bf16x8 pf = __builtin_bit_cast(bf16x8, pwv);
; #pragma unroll
;                 for (int c = 0; c < 4; ++c) { const LAS bf16* vp = Vl + ((a + 2 * j2) * 16 + 4 * fq + q4) * KP + 16 * c + 4 * p4;
;                     const s16x4 lo = tr_read(vp), hi = tr_read(vp + 16 * KP);
;                     const bf16x8 vf = (bf16x8){lo[0], lo[1], lo[2], lo[3], hi[0], hi[1], hi[2], hi[3]};
;                     oacc[c] = __builtin_amdgcn_mfma_f32_16x16x32_bf16(vf, pf, oacc[c], 0, 0, 0); }
	v_mul_f32_e32 v95, 0x3fb8aa3b, v95
	v_add_f32_e32 v81, v82, v81
	v_exp_f32_e32 v94, v94
	v_exp_f32_e32 v129, v95
	v_sub_f32_e32 v95, v135, v76
	v_add_f32_e32 v81, v83, v81
	v_mul_f32_e32 v95, 0x3fb8aa3b, v95
	v_add_f32_e32 v81, v92, v81
	v_exp_f32_e32 v148, v95
	v_sub_f32_e32 v95, v136, v76
	v_add_f32_e32 v81, v93, v81
	v_mul_f32_e32 v95, 0x3fb8aa3b, v95
	v_add_f32_e32 v81, v94, v81
	v_exp_f32_e32 v149, v95
	v_sub_f32_e32 v95, v137, v76
	v_add_f32_e32 v81, v98, v81
	v_mul_f32_e32 v95, 0x3fb8aa3b, v95
	v_add_f32_e32 v81, v99, v81
	v_exp_f32_e32 v150, v95
	v_sub_f32_e32 v95, v134, v76
	v_add_f32_e32 v81, v115, v81
	v_mul_f32_e32 v95, 0x3fb8aa3b, v95
	v_add_f32_e32 v81, v125, v81
	v_exp_f32_e32 v151, v95
	v_sub_f32_e32 v95, v139, v76
	v_add_f32_e32 v81, v126, v81
	v_mul_f32_e32 v95, 0x3fb8aa3b, v95
	v_add_f32_e32 v81, v127, v81
	v_exp_f32_e32 v152, v95
	v_sub_f32_e32 v95, v140, v76
	v_add_f32_e32 v81, v128, v81
	v_mul_f32_e32 v95, 0x3fb8aa3b, v95
	v_add_f32_e32 v81, v129, v81
	v_exp_f32_e32 v153, v95
	v_sub_f32_e32 v95, v141, v76
	v_sub_f32_e32 v88, v88, v76
	v_add_f32_e32 v81, v148, v81
	v_mul_f32_e32 v95, 0x3fb8aa3b, v95
	v_mul_f32_e32 v88, 0x3fb8aa3b, v88
	v_add_f32_e32 v81, v149, v81
	v_exp_f32_e32 v154, v95
	v_sub_f32_e32 v95, v138, v76
	v_exp_f32_e32 v156, v88
	v_sub_f32_e32 v88, v89, v76
	v_add_f32_e32 v81, v150, v81
	v_mul_f32_e32 v95, 0x3fb8aa3b, v95
	v_mul_f32_e32 v88, 0x3fb8aa3b, v88
	v_add_f32_e32 v81, v151, v81
	v_exp_f32_e32 v155, v95
	v_exp_f32_e32 v157, v88
	v_sub_f32_e32 v88, v90, v76
	v_add_f32_e32 v81, v152, v81
	v_mul_f32_e32 v88, 0x3fb8aa3b, v88
	v_sub_f32_e32 v84, v84, v76
	v_add_f32_e32 v81, v153, v81
	v_exp_f32_e32 v158, v88
	v_sub_f32_e32 v88, v91, v76
	v_mul_f32_e32 v84, 0x3fb8aa3b, v84
	v_add_f32_e32 v81, v154, v81
	v_mul_f32_e32 v88, 0x3fb8aa3b, v88
	v_exp_f32_e32 v160, v84
	v_sub_f32_e32 v84, v85, v76
	v_add_f32_e32 v81, v155, v81
	v_exp_f32_e32 v159, v88
	v_mul_f32_e32 v84, 0x3fb8aa3b, v84
	v_add_f32_e32 v81, v156, v81
	v_exp_f32_e32 v161, v84
	v_sub_f32_e32 v84, v86, v76
	v_add_f32_e32 v81, v157, v81
	v_mul_f32_e32 v84, 0x3fb8aa3b, v84
	v_add_f32_e32 v81, v158, v81
	v_exp_f32_e32 v162, v84
	v_add_f32_e32 v81, v159, v81
	v_add_f32_e32 v81, v160, v81
	v_add_f32_e32 v81, v161, v81
	v_bfe_u32 v85, v82, 16, 1
	v_bfe_u32 v86, v79, 16, 1
	v_add_f32_e32 v130, v162, v81
	v_sub_f32_e32 v81, v87, v76
	v_add3_u32 v86, v79, v86, s39
	v_add3_u32 v79, v82, v85, s39
	v_bfe_u32 v85, v80, 16, 1
	v_bfe_u32 v87, v83, 16, 1
	v_bfe_u32 v84, v92, 16, 1
	v_add3_u32 v83, v83, v87, s39
	v_add3_u32 v80, v80, v85, s39
	v_mul_f32_e32 v81, 0x3fb8aa3b, v81
	v_add3_u32 v82, v92, v84, s39
	v_bfe_u32 v84, v78, 16, 1
	v_bfe_u32 v88, v93, 16, 1
	v_lshrrev_b32_e32 v87, 16, v80
	v_lshrrev_b32_e32 v80, 16, v83
	v_exp_f32_e32 v163, v81
	v_bfe_u32 v81, v94, 16, 1
	v_add3_u32 v88, v93, v88, s39
	v_add3_u32 v78, v78, v84, s39
	v_and_or_b32 v80, v82, s38, v80
	v_or_b32_e32 v82, s28, v121
	v_sub_f32_e32 v131, v142, v76
	v_add3_u32 v81, v94, v81, s39
	v_lshrrev_b32_e32 v78, 16, v78
	v_lshrrev_b32_e32 v83, 16, v88
	v_mad_u64_u32 v[96:97], s[18:19], v82, s42, v[110:111]
	v_mul_f32_e32 v131, 0x3fb8aa3b, v131
	v_and_or_b32 v81, v81, s38, v83
	ds_read_b64_tr_b16 v[84:85], v96 offset:41472
	ds_read_b64_tr_b16 v[82:83], v96 offset:39168
	v_and_or_b32 v79, v79, s38, v87
	v_and_or_b32 v78, v86, s38, v78
	ds_read_b64_tr_b16 v[88:89], v96 offset:41504
	ds_read_b64_tr_b16 v[86:87], v96 offset:39200
	ds_read_b64_tr_b16 v[90:91], v96 offset:39232
	ds_read_b64_tr_b16 v[94:95], v96 offset:39264
	ds_read_b64_tr_b16 v[92:93], v96 offset:41536
	ds_read_b64_tr_b16 v[96:97], v96 offset:41568
	v_exp_f32_e32 v142, v131
	v_sub_f32_e32 v131, v143, v76
	v_mul_f32_e32 v131, 0x3fb8aa3b, v131
	v_exp_f32_e32 v143, v131
	v_add_f32_e32 v130, v163, v130
	s_waitcnt lgkmcnt(6)
	v_mfma_f32_16x16x32_bf16 v[82:85], v[82:85], v[78:81], 0
	v_add_f32_e32 v130, v142, v130
	v_add_f32_e32 v164, v143, v130
	v_sub_f32_e32 v77, v77, v76
	s_waitcnt lgkmcnt(4)
	v_mfma_f32_16x16x32_bf16 v[86:89], v[86:89], v[78:81], 0
	v_mul_f32_e32 v77, 0x3fb8aa3b, v77
	v_exp_f32_e32 v77, v77
	s_waitcnt lgkmcnt(1)
	v_mfma_f32_16x16x32_bf16 v[90:93], v[90:93], v[78:81], 0
	s_waitcnt lgkmcnt(0)
	v_mfma_f32_16x16x32_bf16 v[78:81], v[94:97], v[78:81], 0
	v_bfe_u32 v95, v127, 16, 1
	v_bfe_u32 v97, v99, 16, 1
	v_add3_u32 v130, v99, v97, s39
	v_add3_u32 v95, v127, v95, s39
	v_bfe_u32 v97, v115, 16, 1
	v_bfe_u32 v127, v128, 16, 1
	v_bfe_u32 v94, v129, 16, 1
	v_bfe_u32 v96, v125, 16, 1
	v_add3_u32 v127, v128, v127, s39
	v_add3_u32 v97, v115, v97, s39
	v_add3_u32 v125, v125, v96, s39
	v_add3_u32 v94, v129, v94, s39
	v_bfe_u32 v96, v98, 16, 1
	v_bfe_u32 v99, v126, 16, 1
	v_lshrrev_b32_e32 v131, 16, v97
	v_lshrrev_b32_e32 v97, 16, v127
	v_add3_u32 v99, v126, v99, s39
	v_add3_u32 v96, v98, v96, s39
	v_and_or_b32 v97, v94, s38, v97
	v_or_b32_e32 v94, s49, v121
	v_lshrrev_b32_e32 v115, 16, v96
	v_lshrrev_b32_e32 v96, 16, v99
	v_mad_u64_u32 v[98:99], s[18:19], v94, s42, v[110:111]
	v_and_or_b32 v96, v95, s38, v96
	ds_read_b64_tr_b16 v[128:129], v98 offset:41472
	ds_read_b64_tr_b16 v[126:127], v98 offset:39168
	v_and_or_b32 v95, v125, s38, v131
	v_and_or_b32 v94, v130, s38, v115
	ds_read_b64_tr_b16 v[132:133], v98 offset:41504
	ds_read_b64_tr_b16 v[130:131], v98 offset:39200
	ds_read_b64_tr_b16 v[134:135], v98 offset:39232
	ds_read_b64_tr_b16 v[138:139], v98 offset:39264
	ds_read_b64_tr_b16 v[136:137], v98 offset:41536
	ds_read_b64_tr_b16 v[140:141], v98 offset:41568
	v_sub_f32_e32 v98, v144, v76
	v_mul_f32_e32 v98, 0x3fb8aa3b, v98
	v_exp_f32_e32 v115, v98
	v_sub_f32_e32 v98, v113, v76
	s_waitcnt lgkmcnt(6)
; #define LAS __attribute__((address_space(3)))
; __device__ __forceinline__ unsigned pk2(float lo, float hi) { return f2bf(lo) | (f2bf(hi) << 16); }
; __device__ __forceinline__ s16x4 tr_read(const LAS bf16* p) { return __builtin_bit_cast(s16x4, __builtin_amdgcn_ds_read_tr16_b64_v4i16((LAS s16x4*)p)); }
; __device__ __forceinline__ void attn_phase(LAS unsigned char* lds, const bf16* QKV, bf16* O, const float* rope, const float* sinks) {
;     ...
;             for (int j = 0; j < 10; ++j)
; #pragma unroll
;                 for (int e = 0; e < 4; ++e) { const float p = __expf(sc[j][e] - mx); sc[j][e] = p; l += p; }
;             l += __shfl_xor(l, 16); l += __shfl_xor(l, 32); l += __expf(sink - mx);
;             const float rl = 1.0f / l;
;             f32x4 oacc[4];
; #pragma unroll
;             for (int c = 0; c < 4; ++c) oacc[c] = (f32x4){0.f, 0.f, 0.f, 0.f};
; #pragma unroll
;             for (int j2 = 0; j2 < 5; ++j2) {
;                 u32x4 pwv; pwv.x = pk2(sc[2 * j2][0], sc[2 * j2][1]); pwv.y = pk2(sc[2 * j2][2], sc[2 * j2][3]); pwv.z = pk2(sc[2 * j2 + 1][0], sc[2 * j2 + 1][1]); pwv.w = pk2(sc[2 * j2 + 1][2], sc[2 * j2 + 1][3]);
;                 const bf16x8 pf = __builtin_bit_cast(bf16x8, pwv);
; #pragma unroll
;                 for (int c = 0; c < 4; ++c) { const LAS bf16* vp = Vl + ((a + 2 * j2) * 16 + 4 * fq + q4) * KP + 16 * c + 4 * p4;
;                     const s16x4 lo = tr_read(vp), hi = tr_read(vp + 16 * KP);
;                     const bf16x8 vf = (bf16x8){lo[0], lo[1], lo[2], lo[3], hi[0], hi[1], hi[2], hi[3]};
;                     oacc[c] = __builtin_amdgcn_mfma_f32_16x16x32_bf16(vf, pf, oacc[c], 0, 0, 0); }
;             }
	v_mfma_f32_16x16x32_bf16 v[82:85], v[126:129], v[94:97], v[82:85]
	v_mul_f32_e32 v98, 0x3fb8aa3b, v98
	v_exp_f32_e32 v113, v98
	v_sub_f32_e32 v98, v145, v76
	s_waitcnt lgkmcnt(4)
	v_mfma_f32_16x16x32_bf16 v[86:89], v[130:133], v[94:97], v[86:89]
	v_bfe_u32 v99, v154, 16, 1
	v_mul_f32_e32 v98, 0x3fb8aa3b, v98
	v_add3_u32 v99, v154, v99, s39
	s_waitcnt lgkmcnt(1)
	v_mfma_f32_16x16x32_bf16 v[90:93], v[134:137], v[94:97], v[90:93]
	v_exp_f32_e32 v125, v98
	v_bfe_u32 v98, v152, 16, 1
	v_add3_u32 v98, v152, v98, s39
	s_waitcnt lgkmcnt(0)
	v_mfma_f32_16x16x32_bf16 v[78:81], v[138:141], v[94:97], v[78:81]
	v_bfe_u32 v97, v149, 16, 1
	v_add3_u32 v130, v149, v97, s39
	v_bfe_u32 v97, v150, 16, 1
	v_bfe_u32 v94, v155, 16, 1
	v_bfe_u32 v96, v151, 16, 1
	v_add3_u32 v97, v150, v97, s39
	v_add3_u32 v131, v151, v96, s39
	v_add3_u32 v94, v155, v94, s39
	v_bfe_u32 v96, v148, 16, 1
	v_lshrrev_b32_e32 v133, 16, v97
	v_lshrrev_b32_e32 v97, 16, v99
	v_bfe_u32 v95, v153, 16, 1
	v_add3_u32 v96, v148, v96, s39
	v_and_or_b32 v97, v94, s38, v97
	v_or_b32_e32 v94, s48, v121
	v_add3_u32 v95, v153, v95, s39
	v_lshrrev_b32_e32 v132, 16, v96
	v_lshrrev_b32_e32 v96, 16, v98
	v_mad_u64_u32 v[98:99], s[18:19], v94, s42, v[110:111]
	v_and_or_b32 v96, v95, s38, v96
	ds_read_b64_tr_b16 v[128:129], v98 offset:41472
	ds_read_b64_tr_b16 v[126:127], v98 offset:39168
	v_and_or_b32 v95, v131, s38, v133
	v_and_or_b32 v94, v130, s38, v132
	ds_read_b64_tr_b16 v[132:133], v98 offset:41504
	ds_read_b64_tr_b16 v[130:131], v98 offset:39200
	ds_read_b64_tr_b16 v[134:135], v98 offset:39232
	ds_read_b64_tr_b16 v[138:139], v98 offset:39264
	ds_read_b64_tr_b16 v[136:137], v98 offset:41536
	ds_read_b64_tr_b16 v[140:141], v98 offset:41568
	v_add_f32_e32 v98, v115, v164
	s_waitcnt lgkmcnt(6)
	v_mfma_f32_16x16x32_bf16 v[82:85], v[126:129], v[94:97], v[82:85]
	v_add_f32_e32 v98, v113, v98
	v_add_f32_e32 v144, v125, v98
	v_sub_f32_e32 v98, v146, v76
	s_waitcnt lgkmcnt(4)
	v_mfma_f32_16x16x32_bf16 v[86:89], v[130:133], v[94:97], v[86:89]
	v_bfe_u32 v99, v162, 16, 1
	v_mul_f32_e32 v98, 0x3fb8aa3b, v98
	v_add3_u32 v99, v162, v99, s39
	s_waitcnt lgkmcnt(1)
	v_mfma_f32_16x16x32_bf16 v[90:93], v[134:137], v[94:97], v[90:93]
	v_exp_f32_e32 v145, v98
	v_bfe_u32 v98, v160, 16, 1
	v_add3_u32 v98, v160, v98, s39
	s_waitcnt lgkmcnt(0)
	v_mfma_f32_16x16x32_bf16 v[78:81], v[138:141], v[94:97], v[78:81]
	v_bfe_u32 v97, v157, 16, 1
	v_add3_u32 v130, v157, v97, s39
	v_bfe_u32 v97, v158, 16, 1
	v_bfe_u32 v94, v163, 16, 1
	v_bfe_u32 v96, v159, 16, 1
	v_add3_u32 v97, v158, v97, s39
	v_add3_u32 v131, v159, v96, s39
	v_add3_u32 v94, v163, v94, s39
	v_bfe_u32 v96, v156, 16, 1
	v_lshrrev_b32_e32 v133, 16, v97
	v_lshrrev_b32_e32 v97, 16, v99
	v_bfe_u32 v95, v161, 16, 1
	v_add3_u32 v96, v156, v96, s39
	v_and_or_b32 v97, v94, s38, v97
	v_or_b32_e32 v94, s47, v121
	v_add3_u32 v95, v161, v95, s39
	v_lshrrev_b32_e32 v132, 16, v96
	v_lshrrev_b32_e32 v96, 16, v98
	v_mad_u64_u32 v[98:99], s[18:19], v94, s42, v[110:111]
	v_and_or_b32 v96, v95, s38, v96
	ds_read_b64_tr_b16 v[128:129], v98 offset:41472
	ds_read_b64_tr_b16 v[126:127], v98 offset:39168
	v_and_or_b32 v95, v131, s38, v133
	v_and_or_b32 v94, v130, s38, v132
	ds_read_b64_tr_b16 v[132:133], v98 offset:41504
	ds_read_b64_tr_b16 v[130:131], v98 offset:39200
	ds_read_b64_tr_b16 v[134:135], v98 offset:39232
	ds_read_b64_tr_b16 v[138:139], v98 offset:39264
	ds_read_b64_tr_b16 v[136:137], v98 offset:41536
	ds_read_b64_tr_b16 v[140:141], v98 offset:41568
	v_sub_f32_e32 v98, v147, v76
	v_mul_f32_e32 v98, 0x3fb8aa3b, v98
	v_exp_f32_e32 v98, v98
	v_add_f32_e32 v99, v77, v144
	v_add_f32_e32 v99, v145, v99
	s_waitcnt lgkmcnt(6)
	v_mfma_f32_16x16x32_bf16 v[82:85], v[126:129], v[94:97], v[82:85]
	v_add_f32_e32 v99, v98, v99
	ds_bpermute_b32 v126, v111, v99
	v_sub_f32_e32 v76, v117, v76
	s_waitcnt lgkmcnt(5)
	v_mfma_f32_16x16x32_bf16 v[86:89], v[130:133], v[94:97], v[86:89]
	v_mul_f32_e32 v76, 0x3fb8aa3b, v76
	v_exp_f32_e32 v76, v76
	s_waitcnt lgkmcnt(0)
; #define LAS __attribute__((address_space(3)))
; __device__ __forceinline__ unsigned pk2(float lo, float hi) { return f2bf(lo) | (f2bf(hi) << 16); }
; __device__ __forceinline__ s16x4 tr_read(const LAS bf16* p) { return __builtin_bit_cast(s16x4, __builtin_amdgcn_ds_read_tr16_b64_v4i16((LAS s16x4*)p)); }
; __device__ __forceinline__ void attn_phase(LAS unsigned char* lds, const bf16* QKV, bf16* O, const float* rope, const float* sinks) {
;     ...
;             l += __shfl_xor(l, 16); l += __shfl_xor(l, 32); l += __expf(sink - mx);
;             const float rl = 1.0f / l;
;             f32x4 oacc[4];
; #pragma unroll
;             for (int c = 0; c < 4; ++c) oacc[c] = (f32x4){0.f, 0.f, 0.f, 0.f};
; #pragma unroll
;             for (int j2 = 0; j2 < 5; ++j2) {
;                 u32x4 pwv; pwv.x = pk2(sc[2 * j2][0], sc[2 * j2][1]); pwv.y = pk2(sc[2 * j2][2], sc[2 * j2][3]); pwv.z = pk2(sc[2 * j2 + 1][0], sc[2 * j2 + 1][1]); pwv.w = pk2(sc[2 * j2 + 1][2], sc[2 * j2 + 1][3]);
;                 const bf16x8 pf = __builtin_bit_cast(bf16x8, pwv);
; #pragma unroll
;                 for (int c = 0; c < 4; ++c) { const LAS bf16* vp = Vl + ((a + 2 * j2) * 16 + 4 * fq + q4) * KP + 16 * c + 4 * p4;
;                     const s16x4 lo = tr_read(vp), hi = tr_read(vp + 16 * KP);
;                     const bf16x8 vf = (bf16x8){lo[0], lo[1], lo[2], lo[3], hi[0], hi[1], hi[2], hi[3]};
;                     oacc[c] = __builtin_amdgcn_mfma_f32_16x16x32_bf16(vf, pf, oacc[c], 0, 0, 0); }
;             }
;             bf16* op = O + qrow * D + (qrow >> 8) * adjo + qh * 64 + 4 * fq;
; #pragma unroll
;             for (int c = 0; c < 4; ++c) { u32x2 w; w.x = pk2(oacc[c][0] * rl, oacc[c][1] * rl); w.y = pk2(oacc[c][2] * rl, oacc[c][3] * rl); *(u32x2*)(op + 16 * c) = w; }
	v_add_f32_e32 v144, v99, v126
	v_mfma_f32_16x16x32_bf16 v[90:93], v[134:137], v[94:97], v[90:93]
	v_mfma_f32_16x16x32_bf16 v[78:81], v[138:141], v[94:97], v[78:81]
	v_bfe_u32 v95, v77, 16, 1
	v_bfe_u32 v96, v113, 16, 1
	v_bfe_u32 v97, v143, 16, 1
	v_add3_u32 v130, v143, v97, s39
	v_add3_u32 v113, v113, v96, s39
	v_add3_u32 v77, v77, v95, s39
	v_bfe_u32 v95, v142, 16, 1
	v_bfe_u32 v96, v115, 16, 1
	v_bfe_u32 v97, v125, 16, 1
	v_bfe_u32 v94, v98, 16, 1
	v_add3_u32 v97, v125, v97, s39
	v_add3_u32 v96, v115, v96, s39
	v_add3_u32 v95, v142, v95, s39
	v_add3_u32 v94, v98, v94, s39
	v_bfe_u32 v98, v145, 16, 1
	v_lshrrev_b32_e32 v115, 16, v95
	v_lshrrev_b32_e32 v95, 16, v96
	v_lshrrev_b32_e32 v96, 16, v97
	v_add3_u32 v98, v145, v98, s39
	v_and_or_b32 v96, v77, s38, v96
	v_or_b32_e32 v77, s46, v121
	v_lshrrev_b32_e32 v97, 16, v98
	v_mad_u64_u32 v[98:99], s[18:19], v77, s42, v[110:111]
	ds_bpermute_b32 v77, v120, v144
	v_and_or_b32 v95, v113, s38, v95
	v_and_or_b32 v97, v94, s38, v97
	ds_read_b64_tr_b16 v[128:129], v98 offset:41472
	ds_read_b64_tr_b16 v[126:127], v98 offset:39168
	v_and_or_b32 v94, v130, s38, v115
	s_waitcnt lgkmcnt(2)
	v_add_f32_e32 v77, v144, v77
	v_add_f32_e32 v113, v76, v77
	ds_read_b64_tr_b16 v[132:133], v98 offset:41504
	ds_read_b64_tr_b16 v[130:131], v98 offset:39200
	ds_read_b64_tr_b16 v[134:135], v98 offset:39232
	ds_read_b64_tr_b16 v[138:139], v98 offset:39264
	ds_read_b64_tr_b16 v[136:137], v98 offset:41536
	ds_read_b64_tr_b16 v[140:141], v98 offset:41568
	v_div_scale_f32 v115, s[18:19], v113, v113, 1.0
	v_rcp_f32_e32 v125, v115
	s_waitcnt lgkmcnt(0)
	v_mfma_f32_16x16x32_bf16 v[76:79], v[138:141], v[94:97], v[78:81]
	v_lshl_add_u64 v[98:99], v[44:45], 0, s[28:29]
	s_nop 1
	v_fma_f32 v80, -v115, v125, 1.0
	v_fmac_f32_e32 v125, v80, v125
	v_div_scale_f32 v80, vcc, 1.0, v113, 1.0
	v_mul_f32_e32 v81, v80, v125
	v_mfma_f32_16x16x32_bf16 v[82:85], v[126:129], v[94:97], v[82:85]
	v_mfma_f32_16x16x32_bf16 v[86:89], v[130:133], v[94:97], v[86:89]
	v_mfma_f32_16x16x32_bf16 v[90:93], v[134:137], v[94:97], v[90:93]
	v_fma_f32 v94, -v115, v81, v80
	v_fmac_f32_e32 v81, v94, v125
	v_fma_f32 v80, -v115, v81, v80
	v_div_fmas_f32 v80, v80, v125, v81
	v_div_fixup_f32 v80, v80, v113, 1.0
	s_nop 0
	v_mov_b32_e32 v96, v82
	v_mov_b32_e32 v97, v84
	v_pk_mul_f32 v[96:97], v[96:97], v[80:81] op_sel_hi:[1,0]
	v_mov_b32_e32 v84, v83
	v_pk_mul_f32 v[82:83], v[84:85], v[80:81] op_sel_hi:[1,0]
	v_lshlrev_b64 v[94:95], 12, v[98:99]
	v_cvt_pk_bf16_f32 v82, v96, v82
	v_cvt_pk_bf16_f32 v83, v97, v83
	v_lshl_add_u64 v[94:95], v[118:119], 0, v[94:95]
	global_store_dwordx2 v[94:95], v[82:83], off
	v_mov_b32_e32 v82, v86
	v_mov_b32_e32 v83, v88
	v_pk_mul_f32 v[82:83], v[80:81], v[82:83] op_sel_hi:[0,1]
	v_mov_b32_e32 v88, v87
	v_pk_mul_f32 v[84:85], v[80:81], v[88:89] op_sel_hi:[0,1]
	v_cvt_pk_bf16_f32 v82, v82, v84
	v_cvt_pk_bf16_f32 v83, v83, v85
	global_store_dwordx2 v[94:95], v[82:83], off offset:32
	v_mov_b32_e32 v82, v90
	v_mov_b32_e32 v83, v92
	v_pk_mul_f32 v[82:83], v[80:81], v[82:83] op_sel_hi:[0,1]
	v_mov_b32_e32 v92, v91
	v_pk_mul_f32 v[84:85], v[80:81], v[92:93] op_sel_hi:[0,1]
	v_cvt_pk_bf16_f32 v82, v82, v84
	v_cvt_pk_bf16_f32 v83, v83, v85
	global_store_dwordx2 v[94:95], v[82:83], off offset:64
	v_mov_b32_e32 v83, v78
	v_mov_b32_e32 v78, v77
	v_mov_b32_e32 v82, v76
	v_pk_mul_f32 v[76:77], v[80:81], v[78:79] op_sel_hi:[0,1]
	v_pk_mul_f32 v[82:83], v[80:81], v[82:83] op_sel_hi:[0,1]
	v_cvt_pk_bf16_f32 v76, v82, v76
	v_cvt_pk_bf16_f32 v77, v83, v77
	global_store_dwordx2 v[94:95], v[76:77], off offset:96
	v_mov_b64_e32 v[98:99], v[62:63]
	v_mov_b64_e32 v[94:95], v[66:67]
	v_mov_b64_e32 v[90:91], v[70:71]
	v_mov_b64_e32 v[86:87], v[74:75]
	v_mov_b64_e32 v[82:83], v[58:59]
	v_mov_b64_e32 v[78:79], v[54:55]
	v_mov_b64_e32 v[96:97], v[60:61]
	v_mov_b64_e32 v[92:93], v[64:65]
	v_mov_b64_e32 v[88:89], v[68:69]
	v_mov_b64_e32 v[84:85], v[72:73]
	v_mov_b64_e32 v[80:81], v[56:57]
	v_mov_b64_e32 v[76:77], v[52:53]
	s_cbranch_scc1 .LBB0_1740
